# FoX: tile-skip table preloaded to LDS, unit prologue no longer waits on a global round trip before addressing the K/V DMAs
# speedup vs baseline: 1.0015x; 1.0015x over previous
; __device__ __forceinline__ int opaque_tid() { int t = threadIdx.x; asm volatile("" : "+v"(t)); return t; }
; #define BAR_ALL() asm volatile("s_waitcnt vmcnt(0) lgkmcnt(0)\n\ts_barrier" ::: "memory")
; template <bool DRY> __device__ __forceinline__ void fox_phase(const Args& A, char* lds, int vcu, int G) {
;     const bf16* P1 = (const bf16*)(A.ws + WS_BIG); const float* F2 = (const float*)(A.ws + WS_F2); const int* TSv = (const int*)(A.ws + WS_TS);
;     unsigned* cnt = (unsigned*)(A.ws + WS_CNT) + (DRY ? 64 : 0); volatile unsigned* lw = (volatile unsigned*)(lds + BARST_OFF + 16);
;     const int tid = opaque_tid();
;     if (tid == 0) lw[0] = atomicAdd(cnt, 1u);
;     BAR_ALL();
;     int u = __builtin_amdgcn_readfirstlane((int)lw[0]);
.LBB0_1431:
	v_lshlrev_b32_e32 v168, 2, v220
	s_add_u32 s98, s12, 0x1c8400
	s_addc_u32 s99, s13, 0
	v_add_u32_e32 v169, 0x1000, v168
	global_load_dword v170, v168, s[98:99]
	global_load_dword v171, v168, s[98:99] offset:2048
	global_load_dword v172, v169, s[98:99]
	v_add_u32_e32 v168, 0x18000, v168
	s_waitcnt vmcnt(0)
	ds_write_b32 v168, v170
	ds_write_b32 v168, v171 offset:2048
	ds_write_b32 v168, v172 offset:4096
	s_add_u32 s14, s12, 0x1c3800
	v_mov_b32_e32 v0, v220
	s_addc_u32 s15, s13, 0
	s_nop 0
	v_cmp_eq_u32_e64 s[6:7], 0, v0
	s_and_saveexec_b64 s[8:9], s[6:7]
	s_cbranch_execz .LBB0_1433
	v_mov_b32_e32 v2, 1
	v_mov_b64_e32 v[0:1], s[14:15]
	flat_atomic_add v2, v[0:1], v2 sc0
	s_mov_b64 s[0:1], src_shared_base
	s_cmp_lg_u32 s3, -1
	s_cselect_b32 s0, s3, 0
	s_cselect_b32 s1, s1, 0
	v_mov_b32_e32 v0, s0
	v_mov_b32_e32 v1, s1
	s_waitcnt vmcnt(0) lgkmcnt(0)
	flat_store_dword v[0:1], v2 sc0 sc1
	s_waitcnt vmcnt(0)

; __device__ __forceinline__ int opaque_tid() { int t = threadIdx.x; asm volatile("" : "+v"(t)); return t; }
;   #define DMA_K(t,slot) glds16(ksrc+(long)(t)*KVBLK*DM,(unsigned)__builtin_amdgcn_readfirstlane(kdst+(slot)))
; template<int THRL,int MODE,int DM,bool DRY=false> __device__ __forceinline__ void attn_unit(int b,int h,int qb,const bf16*Q,const bf16*__restrict__ K,const bf16*__restrict__ V,bf16*O,const bf16*__restrict__ Z,const float*__restrict__ XP,const int*__restrict__ TS,volatile unsigned*lw,unsigned nxt,cha ...
;   const int tid=opaque_tid(),lane=tid&63,r32=lane&31,hi=lane>>5; const int wid=__builtin_amdgcn_readfirstlane(tid>>6);
;   const long rowbase=(long)b*SEQ; const int q0=qb*QB;
;   const bf16*Qw=Q+(rowbase+q0+wid*QBLK)*DM+h*D;
;   bf16x8 qr[4];
;   #pragma unroll
;   for(int d0=0;d0<4;++d0)qr[d0]=*reinterpret_cast<const bf16x8*>(&Qw[(long)r32*DM+d0*16+hi*8]);
;   const bf16*Kh=K+rowbase*DM+h*D,*Vh=V+rowbase*DM+h*D;
;   const unsigned lds0=(unsigned)(uintptr_t)shm;
;   float*wsf=(float*)(shm+LDS_WS)+wid*64;
;   const bf16*ksrc_=Kh+(long)lane*DM+wid*8; int tskip=0,fixedref=0; const bf16*ksrc=ksrc_;
;   const bf16*vsrc_=Vh+(long)(16*(wid&3)+(lane>>2))*DM+(wid>>2)*32+(lane&3)*8; const bf16*vsrc=vsrc_;
;   const unsigned kdst=lds0+LDS_K+wid*1024, vdst=lds0+LDS_V+wid*1024;
;     ...
;   const int vb0=(int)(lds0+LDS_V)+((lane>>4)&1)*32+(lane&3)*8+(4*hi+((lane&15)>>2))*64;
;   const char*Kbase=shm+LDS_K; bf16x8 kf[8];
;   const lds_cptr shm3=(lds_cptr)shm; const lds_cptr kp0=shm3+LDS_K+hi*1024+r32*16; const lds_cptr vp0=shm3+LDS_V+((lane>>4)&1)*32+(lane&3)*8+(4*hi+((lane&15)>>2))*64;
;   int NT=(q0+QB)/KVBLK;
;   const int qrel=wid*QBLK+r32;
;   unsigned sel=0u;
;   if constexpr(MODE==1){
;     { const int tsv=__builtin_amdgcn_readfirstlane(TS[qb]); tskip=tsv&0xffff; fixedref=(tsv>>16)&1; }
;     ksrc=ksrc_+(long)tskip*KVBLK*DM; vsrc=vsrc_+(long)tskip*KVBLK*DM; NT-=tskip;
;   }
;   const lds_cptr fsl=(lds_cptr)shm+XOFF+16*hi+tskip*256;
;     ...
;   DMA_K(0,0);DMA_V(0,0);DMA_K(1,SLOTB);
; template <bool DRY> __device__ __forceinline__ void fox_phase(const Args& A, char* lds, int vcu, int G) {
;     ...
;     while (u < NB * 24 * 8) {
;         unsigned nxt = 0u; if (tid == 0) nxt = atomicAdd(cnt, 1u);
;         const int qb = 7 - u / 192, bh = u % 192, b = bh / 24, h = bh % 24;
.LBB0_1436:
	v_mov_b32_e32 v206, 0
	s_and_saveexec_b64 s[8:9], s[6:7]
	s_cbranch_execz .LBB0_1438
	v_mov_b64_e32 v[0:1], s[14:15]
	global_atomic_add v206, v[0:1], v195, off sc0
.LBB0_1438:
	s_or_b64 exec, exec, s[8:9]
	s_mul_hi_i32 s8, s10, 0xd5555555
	s_lshr_b32 s9, s8, 31
	s_ashr_i32 s85, s8, 5
	s_mul_hi_i32 s8, s10, 0x2aaaaaab
	s_add_i32 s85, s85, s9
	s_lshr_b32 s9, s8, 31
	s_lshr_b32 s8, s8, 5
	s_add_i32 s8, s8, s9
	s_mulk_i32 s8, 0xc0
	s_sub_i32 s60, s10, s8
	s_sext_i32_i16 s8, s60
	s_mulk_i32 s8, 0x2aab
	s_lshr_b32 s9, s8, 31
	s_ashr_i32 s8, s8, 18
	s_add_i32 s58, s8, s9
	s_mul_i32 s8, s58, 24
	s_sub_i32 s8, s60, s8
	s_sext_i32_i16 s10, s8
	s_lshl_b32 s8, s60, 3
	s_ashr_i32 s9, s8, 31
	s_add_i32 s16, s85, 7
	s_lshl_b64 s[8:9], s[8:9], 2
	s_add_u32 s61, s18, s8
	v_mov_b32_e32 v207, v220
	s_addc_u32 s66, s33, s9
	s_ashr_i32 s59, s58, 31
	v_readfirstlane_b32 s88, v207
	s_ashr_i32 s81, s88, 6
	s_lshl_b64 s[8:9], s[58:59], 11
	s_lshl_b32 s91, s16, 8
	s_add_u32 s8, s8, s91
	s_addc_u32 s9, s9, 0
	s_lshl_b32 s92, s81, 5
	s_ashr_i32 s11, s92, 31
	s_add_u32 s8, s8, s92
	s_addc_u32 s9, s9, s11
	s_mulk_i32 s9, 0x1c00
	s_mul_hi_u32 s11, s8, 0x1c00
	s_add_i32 s9, s11, s9
	s_mulk_i32 s8, 0x1c00
	s_lshl_b64 s[52:53], s[8:9], 1
	s_add_u32 s11, s0, s52
	s_addc_u32 s51, s1, s53
	s_lshl_b32 s8, s10, 6
	s_ashr_i32 s9, s8, 31
	s_lshl_b64 s[54:55], s[8:9], 1
	s_add_u32 s50, s11, s54
	s_addc_u32 s51, s51, s55
	s_mul_i32 s11, s58, 0x1c00000
	s_mul_hi_i32 s10, s58, 0x1c00000
	s_add_u32 s8, s42, s11
	s_addc_u32 s9, s43, s10
	s_add_u32 s8, s8, s54
	s_addc_u32 s9, s9, s55
	s_add_u32 s11, s71, s11
	s_addc_u32 s10, s72, s10
	s_add_u32 s62, s11, s54
	s_addc_u32 s63, s10, s55
	s_ashr_i32 s10, s88, 3
	s_lshl_b32 s56, s81, 3
	s_andn2_b32 s10, s10, 31
	s_ashr_i32 s57, s56, 31
	s_lshl_b32 s67, s81, 4
	s_ashr_i32 s11, s10, 31
	s_lshl_b32 s59, s81, 10
	s_cmp_lg_u32 0, -1
	s_cselect_b32 s64, 0, 0
	s_add_i32 s83, s59, s64
	s_add_i32 s84, s83, 0x6000
	s_add_i32 s90, s91, 0x100
	s_lshl_b64 s[64:65], s[16:17], 2
	s_add_u32 s64, s61, s64
	s_addc_u32 s65, s66, s65
	v_mov_b64_e32 v[0:1], s[64:65]
	s_sub_u32 s98, s64, s18
	s_add_u32 s98, s98, 0x18000
	v_mov_b32_e32 v6, s98
	ds_read_b32 v6, v6
	v_and_b32_e32 v208, 31, v207
	v_mul_u32_u24_e32 v0, 0x1c00, v208
	v_bfe_u32 v209, v207, 5, 1
	v_lshlrev_b32_e32 v0, 1, v0
	v_lshl_or_b32 v192, v209, 4, v0
	v_lshl_add_u64 v[0:1], s[50:51], 0, v[192:193]
	global_load_dwordx4 v[108:111], v[0:1], off
	global_load_dwordx4 v[104:107], v[0:1], off offset:32
	global_load_dwordx4 v[100:103], v[0:1], off offset:64
	global_load_dwordx4 v[96:99], v[0:1], off offset:96
	v_bfe_u32 v4, v207, 2, 4
	v_and_b32_e32 v210, 63, v207
	v_and_or_b32 v4, s67, 48, v4
	v_mul_u32_u24_e32 v2, 0x1c00, v210
	v_mul_u32_u24_e32 v4, 0x1c00, v4
	v_mov_b32_e32 v173, v193
	v_lshlrev_b32_e32 v212, 3, v207
	v_lshlrev_b32_e32 v192, 1, v2
	v_lshlrev_b32_e32 v172, 1, v4
	v_and_b32_e32 v211, 24, v212
	v_lshl_add_u64 v[2:3], s[8:9], 0, v[192:193]
	v_lshl_add_u64 v[4:5], s[62:63], 0, v[172:173]
	v_mov_b32_e32 v1, v193
	v_lshlrev_b32_e32 v0, 1, v211
	v_lshl_add_u64 v[2:3], s[56:57], 1, v[2:3]
	v_lshl_add_u64 v[4:5], s[10:11], 1, v[4:5]
	v_lshl_add_u64 v[0:1], v[4:5], 0, v[0:1]
	s_add_i32 s61, s83, 0x2000
	s_waitcnt lgkmcnt(0)
	v_readfirstlane_b32 s89, v6
	s_and_b32 s87, s89, 0xffff
	s_lshl_b32 s16, s87, 6
	v_mad_u64_u32 v[66:67], s[8:9], s16, v204, v[2:3]
	s_mov_b32 s8, m0
	s_mov_b32 m0, s83
	s_nop 0
	global_load_lds_dwordx4 v[66:67], off
	s_mov_b32 m0, s8
	v_lshl_add_u64 v[2:3], v[66:67], 0, s[24:25]
	v_mad_u64_u32 v[64:65], s[8:9], s16, v204, v[0:1]
	s_mov_b32 s8, m0
	s_mov_b32 m0, s84
	s_nop 0
	global_load_lds_dwordx4 v[64:65], off
	s_mov_b32 m0, s8
	v_lshl_add_u64 v[0:1], v[66:67], 0, s[22:23]
	s_mov_b32 s8, m0
	s_mov_b32 m0, s61
	s_nop 0
	global_load_lds_dwordx4 v[0:1], off
	s_mov_b32 m0, s8
	s_add_i32 s8, s83, 0x4000
	s_mov_b32 s9, m0
	s_mov_b32 m0, s8
	s_nop 0
	global_load_lds_dwordx4 v[2:3], off
	s_mov_b32 m0, s9
	v_add_u32_e32 v0, s16, v207
	s_lshl_b32 s86, s87, 8
	v_cmp_gt_i32_e32 vcc, s90, v0
	s_and_saveexec_b64 s[8:9], vcc
	s_cbranch_execz .LBB0_1451
	v_add_u32_e32 v1, 0x200, v0
	v_max_i32_e32 v2, s90, v1
	v_xad_u32 v2, v207, -1, v2
	s_ashr_i32 s61, s60, 31
	v_subrev_u32_e32 v2, s16, v2
	s_lshl_b64 s[60:61], s[60:61], 13
	v_cmp_lt_u32_e32 vcc, s75, v2
	s_mov_b64 s[64:65], -1
	s_and_saveexec_b64 s[62:63], vcc
	s_cbranch_execz .LBB0_1448
	v_lshrrev_b32_e32 v4, 9, v2
	v_add_u32_e32 v2, -1, v4
	s_add_u32 s64, s4, s60
	v_lshrrev_b32_e32 v3, 1, v2
	s_addc_u32 s65, s5, s61
	v_add_u32_e32 v5, 1, v3
	v_cmp_lt_u32_e32 vcc, 13, v2
	v_mov_b32_e32 v8, 0
	v_mov_b64_e32 v[2:3], v[0:1]
	s_and_saveexec_b64 s[66:67], vcc
	s_cbranch_execz .LBB0_1444
	s_add_i32 s68, s86, 0
	s_add_i32 s68, s68, 0x15000
	v_and_b32_e32 v6, -8, v5
	v_lshl_add_u32 v7, v207, 2, s68
	s_mov_b32 s93, 0
	s_mov_b64 s[68:69], 0
	v_mov_b64_e32 v[2:3], v[0:1]
